# speedup vs baseline: 1.0158x; 1.0054x over previous
;     __device__ __forceinline__ void operator()(const f32x4 (&acc)[2][2][4][2], const Unit& u, int wr, int wc, int fr, int fq) const {
;         const int row0 = u.pm * BM + wr * 64 + fr;
; #pragma unroll
;         for (int bj = 0; bj < 2; ++bj) {
;             const int col0 = u.pn * BM + bj * HALF + wc * 32 + 8 * fq;
;             const f32x4 g0 = *(const f32x4*)(gate + col0), g1 = *(const f32x4*)(gate + col0 + 4);
; #pragma unroll
;             for (int ai = 0; ai < 2; ++ai) {
; #pragma unroll
;                 for (int m = 0; m < 4; ++m) {
;                     const size_t off = (size_t)(row0 + ai * HALF + m * 16) * DM + col0;
;                     const f32x4 x0 = *(const f32x4*)(xprev + off), x1 = *(const f32x4*)(xprev + off + 4);
;                     *(f32x4*)(xout + off) = x0 + g0 * acc[ai][bj][m][0]; *(f32x4*)(xout + off + 4) = x1 + g1 * acc[ai][bj][m][1];
;                 }
;             }
;             asm volatile("" ::: "memory");
;         }
;     }
.LBB0_492:
	v_lshl_add_u32 v154, s20, 8, v156
	v_lshl_or_b32 v155, s21, 8, v158
	v_lshl_add_u32 v154, v154, 11, v155
	v_lshlrev_b32_e32 v154, 2, v154
	v_lshlrev_b32_e32 v155, 2, v155
	global_load_dwordx4 v[128:131], v155, s[8:9] offset:16
	global_load_dwordx4 v[132:135], v155, s[8:9]
	global_load_dwordx4 v[150:153], v155, s[8:9] offset:528
	global_load_dwordx4 v[146:149], v155, s[8:9] offset:512
	s_add_u32 s20, s2, 0x0
	s_addc_u32 s21, s3, 0
	global_load_dwordx4 v[160:163], v154, s[20:21] offset:16
	global_load_dwordx4 v[164:167], v154, s[20:21] offset:0
	s_add_u32 s20, s2, 0x20000
	s_addc_u32 s21, s3, 0
	global_load_dwordx4 v[168:171], v154, s[20:21] offset:16
	global_load_dwordx4 v[172:175], v154, s[20:21] offset:0
	s_add_u32 s20, s2, 0x40000
	s_addc_u32 s21, s3, 0
	global_load_dwordx4 v[176:179], v154, s[20:21] offset:16
	global_load_dwordx4 v[188:191], v154, s[20:21] offset:0
	s_add_u32 s20, s2, 0x60000
	s_addc_u32 s21, s3, 0
	global_load_dwordx4 v[196:199], v154, s[20:21] offset:16
	global_load_dwordx4 v[206:209], v154, s[20:21] offset:0
	s_add_u32 s20, s2, 0x100000
	s_addc_u32 s21, s3, 0
	global_load_dwordx4 v[210:213], v154, s[20:21] offset:16
	global_load_dwordx4 v[214:217], v154, s[20:21] offset:0
	s_add_u32 s20, s2, 0x120000
	s_addc_u32 s21, s3, 0
	global_load_dwordx4 v[218:221], v154, s[20:21] offset:16
	global_load_dwordx4 v[222:225], v154, s[20:21] offset:0
	s_waitcnt vmcnt(10)
	v_pk_fma_f32 v[122:123], v[122:123], v[130:131], v[162:163]
	v_pk_fma_f32 v[124:125], v[124:125], v[132:133], v[164:165]
	v_pk_fma_f32 v[120:121], v[120:121], v[128:129], v[160:161]
	v_pk_fma_f32 v[126:127], v[126:127], v[134:135], v[166:167]
	s_add_u32 s20, s0, 0x0
	s_addc_u32 s21, s1, 0
	global_store_dwordx4 v154, v[120:123], s[20:21] offset:16
	global_store_dwordx4 v154, v[124:127], s[20:21] offset:0
	s_add_u32 s20, s2, 0x140000
	s_addc_u32 s21, s3, 0
	global_load_dwordx4 v[160:163], v154, s[20:21] offset:16
	global_load_dwordx4 v[164:167], v154, s[20:21] offset:0
	s_waitcnt vmcnt(12)
	v_pk_fma_f32 v[114:115], v[114:115], v[130:131], v[170:171]
	v_pk_fma_f32 v[116:117], v[116:117], v[132:133], v[172:173]
	v_pk_fma_f32 v[112:113], v[112:113], v[128:129], v[168:169]
	v_pk_fma_f32 v[118:119], v[118:119], v[134:135], v[174:175]
	s_add_u32 s20, s0, 0x20000
	s_addc_u32 s21, s1, 0
	global_store_dwordx4 v154, v[112:115], s[20:21] offset:16
	global_store_dwordx4 v154, v[116:119], s[20:21] offset:0
	s_add_u32 s20, s2, 0x160000
	s_addc_u32 s21, s3, 0
	global_load_dwordx4 v[168:171], v154, s[20:21] offset:16
	global_load_dwordx4 v[172:175], v154, s[20:21] offset:0
	s_waitcnt vmcnt(14)
	v_pk_fma_f32 v[106:107], v[106:107], v[130:131], v[178:179]
	v_pk_fma_f32 v[108:109], v[108:109], v[132:133], v[188:189]
	v_pk_fma_f32 v[104:105], v[104:105], v[128:129], v[176:177]
	v_pk_fma_f32 v[110:111], v[110:111], v[134:135], v[190:191]
	s_add_u32 s20, s0, 0x40000
	s_addc_u32 s21, s1, 0
	global_store_dwordx4 v154, v[104:107], s[20:21] offset:16
	global_store_dwordx4 v154, v[108:111], s[20:21] offset:0
	s_add_u32 s20, s2, 0x0
	s_addc_u32 s21, s3, 0
	global_load_dwordx4 v[176:179], v154, s[20:21] offset:528
	global_load_dwordx4 v[188:191], v154, s[20:21] offset:512
	s_waitcnt vmcnt(16)
	v_pk_fma_f32 v[98:99], v[98:99], v[130:131], v[198:199]
	v_pk_fma_f32 v[100:101], v[100:101], v[132:133], v[206:207]
	v_pk_fma_f32 v[96:97], v[96:97], v[128:129], v[196:197]
	v_pk_fma_f32 v[102:103], v[102:103], v[134:135], v[208:209]
	s_add_u32 s20, s0, 0x60000
	s_addc_u32 s21, s1, 0
	global_store_dwordx4 v154, v[96:99], s[20:21] offset:16
	global_store_dwordx4 v154, v[100:103], s[20:21] offset:0
	s_add_u32 s20, s2, 0x20000
	s_addc_u32 s21, s3, 0
	global_load_dwordx4 v[196:199], v154, s[20:21] offset:528
	global_load_dwordx4 v[206:209], v154, s[20:21] offset:512
	s_waitcnt vmcnt(18)
	v_pk_fma_f32 v[90:91], v[90:91], v[130:131], v[212:213]
	v_pk_fma_f32 v[92:93], v[92:93], v[132:133], v[214:215]
	v_pk_fma_f32 v[88:89], v[88:89], v[128:129], v[210:211]
	v_pk_fma_f32 v[94:95], v[94:95], v[134:135], v[216:217]
	s_add_u32 s20, s0, 0x100000
	s_addc_u32 s21, s1, 0
	global_store_dwordx4 v154, v[88:91], s[20:21] offset:16
	global_store_dwordx4 v154, v[92:95], s[20:21] offset:0
	s_add_u32 s20, s2, 0x40000
	s_addc_u32 s21, s3, 0
	global_load_dwordx4 v[210:213], v154, s[20:21] offset:528
	global_load_dwordx4 v[214:217], v154, s[20:21] offset:512
	s_waitcnt vmcnt(20)
	v_pk_fma_f32 v[82:83], v[82:83], v[130:131], v[220:221]
	v_pk_fma_f32 v[84:85], v[84:85], v[132:133], v[222:223]
	v_pk_fma_f32 v[80:81], v[80:81], v[128:129], v[218:219]
	v_pk_fma_f32 v[86:87], v[86:87], v[134:135], v[224:225]
	s_add_u32 s20, s0, 0x120000
	s_addc_u32 s21, s1, 0
	global_store_dwordx4 v154, v[80:83], s[20:21] offset:16
	global_store_dwordx4 v154, v[84:87], s[20:21] offset:0
	s_add_u32 s20, s2, 0x60000
	s_addc_u32 s21, s3, 0
	global_load_dwordx4 v[218:221], v154, s[20:21] offset:528
	global_load_dwordx4 v[222:225], v154, s[20:21] offset:512
	s_waitcnt vmcnt(20)
; #define PG8_BAR __builtin_amdgcn_s_barrier()
;     __device__ __forceinline__ void operator()(const f32x4 (&acc)[2][2][4][2], const Unit& u, int wr, int wc, int fr, int fq) const {
;         const int row0 = u.pm * BM + wr * 64 + fr;
; #pragma unroll
;         for (int bj = 0; bj < 2; ++bj) {
;             const int col0 = u.pn * BM + bj * HALF + wc * 32 + 8 * fq;
;             const f32x4 g0 = *(const f32x4*)(gate + col0), g1 = *(const f32x4*)(gate + col0 + 4);
; #pragma unroll
;             for (int ai = 0; ai < 2; ++ai) {
; #pragma unroll
;                 for (int m = 0; m < 4; ++m) {
;                     const size_t off = (size_t)(row0 + ai * HALF + m * 16) * DM + col0;
;                     const f32x4 x0 = *(const f32x4*)(xprev + off), x1 = *(const f32x4*)(xprev + off + 4);
;                     *(f32x4*)(xout + off) = x0 + g0 * acc[ai][bj][m][0]; *(f32x4*)(xout + off + 4) = x1 + g1 * acc[ai][bj][m][1];
;                 }
;             }
;             asm volatile("" ::: "memory");
;         }
;     }
; template <class Epi, class Sched>
; __device__ __forceinline__ void gemm_phase(LAS unsigned char* lds, const Gemm g, const Sched& S, const Epi& E, const int tid) {
;     ...
;         if (wr == 0) PG8_BAR;
;         E(acc, cur, wr, wc, fr, fq);
;         if (!has_next) break;
; #pragma unroll
;         for (int a = 0; a < 2; ++a)
; #pragma unroll
;             for (int b = 0; b < 2; ++b)
; #pragma unroll
;                 for (int m = 0; m < 4; ++m)
; #pragma unroll
;                     for (int n = 0; n < 2; ++n) acc[a][b][m][n] = (f32x4){0.f, 0.f, 0.f, 0.f};
;         cur = nxt; cA = nA; cB = nB; ++ui;
;         if (wr == 1) PG8_BAR;
	v_pk_fma_f32 v[74:75], v[74:75], v[130:131], v[162:163]
	v_pk_fma_f32 v[76:77], v[76:77], v[132:133], v[164:165]
	v_pk_fma_f32 v[72:73], v[72:73], v[128:129], v[160:161]
	v_pk_fma_f32 v[78:79], v[78:79], v[134:135], v[166:167]
	s_add_u32 s20, s0, 0x140000
	s_addc_u32 s21, s1, 0
	global_store_dwordx4 v154, v[72:75], s[20:21] offset:16
	global_store_dwordx4 v154, v[76:79], s[20:21] offset:0
	s_add_u32 s20, s2, 0x100000
	s_addc_u32 s21, s3, 0
	global_load_dwordx4 v[160:163], v154, s[20:21] offset:528
	global_load_dwordx4 v[164:167], v154, s[20:21] offset:512
	s_waitcnt vmcnt(20)
	v_pk_fma_f32 v[66:67], v[66:67], v[130:131], v[170:171]
	v_pk_fma_f32 v[68:69], v[68:69], v[132:133], v[172:173]
	v_pk_fma_f32 v[64:65], v[64:65], v[128:129], v[168:169]
	v_pk_fma_f32 v[70:71], v[70:71], v[134:135], v[174:175]
	s_add_u32 s20, s0, 0x160000
	s_addc_u32 s21, s1, 0
	global_store_dwordx4 v154, v[64:67], s[20:21] offset:16
	global_store_dwordx4 v154, v[68:71], s[20:21] offset:0
	s_add_u32 s20, s2, 0x120000
	s_addc_u32 s21, s3, 0
	global_load_dwordx4 v[168:171], v154, s[20:21] offset:528
	global_load_dwordx4 v[172:175], v154, s[20:21] offset:512
	s_waitcnt vmcnt(20)
	v_pk_fma_f32 v[58:59], v[58:59], v[152:153], v[178:179]
	v_pk_fma_f32 v[60:61], v[60:61], v[146:147], v[188:189]
	v_pk_fma_f32 v[56:57], v[56:57], v[150:151], v[176:177]
	v_pk_fma_f32 v[62:63], v[62:63], v[148:149], v[190:191]
	s_add_u32 s20, s0, 0x0
	s_addc_u32 s21, s1, 0
	global_store_dwordx4 v154, v[56:59], s[20:21] offset:528
	global_store_dwordx4 v154, v[60:63], s[20:21] offset:512
	s_add_u32 s20, s2, 0x140000
	s_addc_u32 s21, s3, 0
	global_load_dwordx4 v[176:179], v154, s[20:21] offset:528
	global_load_dwordx4 v[188:191], v154, s[20:21] offset:512
	s_waitcnt vmcnt(20)
	v_pk_fma_f32 v[50:51], v[50:51], v[152:153], v[198:199]
	v_pk_fma_f32 v[52:53], v[52:53], v[146:147], v[206:207]
	v_pk_fma_f32 v[48:49], v[48:49], v[150:151], v[196:197]
	v_pk_fma_f32 v[54:55], v[54:55], v[148:149], v[208:209]
	s_add_u32 s20, s0, 0x20000
	s_addc_u32 s21, s1, 0
	global_store_dwordx4 v154, v[48:51], s[20:21] offset:528
	global_store_dwordx4 v154, v[52:55], s[20:21] offset:512
	s_add_u32 s20, s2, 0x160000
	s_addc_u32 s21, s3, 0
	global_load_dwordx4 v[196:199], v154, s[20:21] offset:528
	global_load_dwordx4 v[206:209], v154, s[20:21] offset:512
	s_waitcnt vmcnt(20)
	v_pk_fma_f32 v[42:43], v[42:43], v[152:153], v[212:213]
	v_pk_fma_f32 v[44:45], v[44:45], v[146:147], v[214:215]
	v_pk_fma_f32 v[40:41], v[40:41], v[150:151], v[210:211]
	v_pk_fma_f32 v[46:47], v[46:47], v[148:149], v[216:217]
	s_add_u32 s20, s0, 0x40000
	s_addc_u32 s21, s1, 0
	global_store_dwordx4 v154, v[40:43], s[20:21] offset:528
	global_store_dwordx4 v154, v[44:47], s[20:21] offset:512
	s_waitcnt vmcnt(18)
	v_pk_fma_f32 v[34:35], v[34:35], v[152:153], v[220:221]
	v_pk_fma_f32 v[36:37], v[36:37], v[146:147], v[222:223]
	v_pk_fma_f32 v[32:33], v[32:33], v[150:151], v[218:219]
	v_pk_fma_f32 v[38:39], v[38:39], v[148:149], v[224:225]
	s_add_u32 s20, s0, 0x60000
	s_addc_u32 s21, s1, 0
	global_store_dwordx4 v154, v[32:35], s[20:21] offset:528
	global_store_dwordx4 v154, v[36:39], s[20:21] offset:512
	s_waitcnt vmcnt(16)
	v_pk_fma_f32 v[26:27], v[26:27], v[152:153], v[162:163]
	v_pk_fma_f32 v[28:29], v[28:29], v[146:147], v[164:165]
	v_pk_fma_f32 v[24:25], v[24:25], v[150:151], v[160:161]
	v_pk_fma_f32 v[30:31], v[30:31], v[148:149], v[166:167]
	s_add_u32 s20, s0, 0x100000
	s_addc_u32 s21, s1, 0
	global_store_dwordx4 v154, v[24:27], s[20:21] offset:528
	global_store_dwordx4 v154, v[28:31], s[20:21] offset:512
	s_waitcnt vmcnt(14)
	v_pk_fma_f32 v[18:19], v[18:19], v[152:153], v[170:171]
	v_pk_fma_f32 v[20:21], v[20:21], v[146:147], v[172:173]
	v_pk_fma_f32 v[16:17], v[16:17], v[150:151], v[168:169]
	v_pk_fma_f32 v[22:23], v[22:23], v[148:149], v[174:175]
	s_add_u32 s20, s0, 0x120000
	s_addc_u32 s21, s1, 0
	global_store_dwordx4 v154, v[16:19], s[20:21] offset:528
	global_store_dwordx4 v154, v[20:23], s[20:21] offset:512
	s_waitcnt vmcnt(12)
	v_pk_fma_f32 v[10:11], v[10:11], v[152:153], v[178:179]
	v_pk_fma_f32 v[12:13], v[12:13], v[146:147], v[188:189]
	v_pk_fma_f32 v[8:9], v[8:9], v[150:151], v[176:177]
	v_pk_fma_f32 v[14:15], v[14:15], v[148:149], v[190:191]
	s_add_u32 s20, s0, 0x140000
	s_addc_u32 s21, s1, 0
	global_store_dwordx4 v154, v[8:11], s[20:21] offset:528
	global_store_dwordx4 v154, v[12:15], s[20:21] offset:512
	s_waitcnt vmcnt(10)
	v_pk_fma_f32 v[2:3], v[2:3], v[152:153], v[198:199]
	v_pk_fma_f32 v[4:5], v[4:5], v[146:147], v[206:207]
	v_pk_fma_f32 v[0:1], v[0:1], v[150:151], v[196:197]
	v_pk_fma_f32 v[6:7], v[6:7], v[148:149], v[208:209]
	s_add_u32 s20, s0, 0x160000
	s_addc_u32 s21, s1, 0
	global_store_dwordx4 v154, v[0:3], s[20:21] offset:528
	global_store_dwordx4 v154, v[4:7], s[20:21] offset:512
	s_mov_b64 s[20:21], -1
	s_andn2_b64 vcc, exec, s[6:7]
	s_cbranch_vccnz .LBB0_481
	s_andn2_b64 vcc, exec, s[4:5]
	s_cbranch_vccnz .LBB0_480
	s_barrier
	s_branch .LBB0_480
